# tail_combine row loops (both FFNs) software-pipelined: next row mapping and loads issued before the current row is stored
# baseline (speedup 1.0000x reference)
; DI void tail_combine(const Prm& p, int Mg, int Ng, const float* part, float alpha, int from_inputs, bf16_t* xn, const float* gnext, float* rss, int gw, int ngw, int lane) {
;     pg8::StaticOrder S; S.init(Mg, Ng, (int)gridDim.x, 0); const int base = S.nwg / (int)gridDim.x, ntail = S.nwg % (int)gridDim.x;
;     for (int it = gw; it < ntail * 256; it += ngw) { const int j = it >> 8, rr = it & 255; pg8::Unit u; S.mapL((long)base * S.G + j, u);
;         const int r = u.pm * 256 + rr, col = u.pn * 256 + 4 * lane; const float* srcp = from_inputs ? x0row(p, r) : xrow(p, r);
;         f32x4 x = srcp ? *(const f32x4*)(srcp + col) : (f32x4){0.f, 0.f, 0.f, 0.f};
.LBB0_814:
	s_or_b64 exec, exec, s[0:1]
	s_waitcnt lgkmcnt(0)
	v_mov_b32_e32 v0, v212
	s_barrier
	v_readlane_b32 s1, v247, 43
	v_readfirstlane_b32 s0, v0
	s_ashr_i32 s0, s0, 6
	s_add_i32 s2, s0, s1
	s_lshl_b32 s0, s33, 8
	s_cmp_ge_i32 s2, s0
	v_writelane_b32 v246, s0, 13
	s_cbranch_scc1 .LBB0_837
	v_and_b32_e32 v0, 63, v0
	v_lshlrev_b32_e32 v4, 4, v0
	v_mov_b32_e32 v5, 0
	v_lshlrev_b32_e32 v12, 2, v0
	v_lshl_add_u64 v[6:7], s[66:67], 0, v[4:5]
	s_mov_b32 s5, 0
	v_cmp_eq_u32_e64 s[0:1], 0, v0
	v_mov_b64_e32 v[8:9], 0x223
	s_ashr_i32 s17, s2, 8
	s_ashr_i32 s4, s17, 31
	v_readlane_b32 s6, v246, 8
	s_add_u32 s6, s6, s17
	v_readlane_b32 s7, v246, 12
	s_addc_u32 s7, s7, s4
	s_nop 0
	v_cmp_gt_i64_e32 vcc, s[6:7], v[8:9]
	s_cbranch_vccnz .Ltcp_823
	s_ashr_i32 s4, s6, 31
	s_lshr_b32 s4, s4, 29
	s_add_i32 s4, s6, s4
	s_and_b32 s7, s4, -8
	s_sub_i32 s10, s6, s7
	s_cmp_gt_i32 s10, 3
	s_mov_b64 s[6:7], -1
	s_cbranch_scc0 .Ltcp_820
	s_mul_i32 s6, s10, 0x44
	s_add_i32 s11, s6, 4
	s_mov_b64 s[6:7], 0

; DI unsigned pk2(float lo, float hi) { f32x2 v = {lo, hi}; bf16x2_t b = __builtin_convertvector(v, bf16x2_t); return __builtin_bit_cast(unsigned, b); }
; DI void tail_combine(const Prm& p, int Mg, int Ng, const float* part, float alpha, int from_inputs, bf16_t* xn, const float* gnext, float* rss, int gw, int ngw, int lane) {
;     ...
;     for (int it = gw; it < ntail * 256; it += ngw) { const int j = it >> 8, rr = it & 255; pg8::Unit u; S.mapL((long)base * S.G + j, u);
;         const int r = u.pm * 256 + rr, col = u.pn * 256 + 4 * lane; const float* srcp = from_inputs ? x0row(p, r) : xrow(p, r);
;         f32x4 x = srcp ? *(const f32x4*)(srcp + col) : (f32x4){0.f, 0.f, 0.f, 0.f};
; #pragma unroll
;         for (int kz = 0; kz < TAIL_KS; ++kz) x = x + *(const f32x4*)(part + (size_t)(j * TAIL_KS + kz) * 65536 + rr * 256 + 4 * lane) * alpha;
;         *(f32x4*)(xrow(p, r) + col) = x;
;         if (xn) { const f32x4 g = *(const f32x4*)(gnext + col); u32x2 w; w.x = pk2(x.x * g.x, x.y * g.y); w.y = pk2(x.z * g.z, x.w * g.w); *(u32x2*)(xn + (size_t)r * D + col) = w;
.Ltcp_834:
	s_lshl_b32 s10, s17, 1
	s_ashr_i32 s11, s10, 31
	s_lshl_b32 s4, s18, 10
	s_lshl_b64 s[12:13], s[10:11], 18
	s_or_b32 s10, s10, 1
	v_lshl_add_u64 v[18:19], v[6:7], 0, s[4:5]
	s_ashr_i32 s11, s10, 31
	v_lshl_add_u64 v[14:15], v[18:19], 0, s[12:13]
	s_lshl_b64 s[10:11], s[10:11], 18
	global_load_dwordx4 v[14:17], v[14:15], off
	v_lshl_add_u64 v[18:19], v[18:19], 0, s[10:11]
	global_load_dwordx4 v[18:21], v[18:19], off
	s_add_i32 s4, s6, 0xffff7800
	s_ashr_i32 s7, s6, 31
	s_cmp_lt_i32 s6, 0x8800
	s_cselect_b32 s11, s7, 0
	s_cselect_b32 s10, s6, s4
	s_cselect_b32 s4, s31, s35
	s_cselect_b32 s12, s30, s34
	s_lshl_b64 s[10:11], s[10:11], 12
	v_readlane_b32 s36, v247, 44
	s_add_u32 s10, s12, s10
	v_lshlrev_b64 v[22:23], 2, v[10:11]
	v_readlane_b32 s42, v247, 50
	v_readlane_b32 s43, v247, 51
	s_addc_u32 s11, s4, s11
	v_readlane_b32 s37, v247, 45
	v_lshl_add_u64 v[24:25], s[42:43], 0, v[22:23]
	v_lshl_add_u64 v[22:23], s[10:11], 0, v[22:23]
	s_lshl_b64 s[10:11], s[6:7], 11
	s_add_u32 s10, s90, s10
	s_addc_u32 s11, s91, s11
	v_lshl_add_u64 v[10:11], v[10:11], 1, s[10:11]
	v_readlane_b32 s38, v247, 46
	v_readlane_b32 s39, v247, 47
	v_readlane_b32 s40, v247, 48
	v_readlane_b32 s41, v247, 49
	v_readlane_b32 s44, v247, 52
	v_readlane_b32 s45, v247, 53
	v_readlane_b32 s46, v247, 54
	v_readlane_b32 s47, v247, 55
	v_readlane_b32 s48, v247, 56
	v_readlane_b32 s49, v247, 57
	v_readlane_b32 s50, v247, 58
	v_readlane_b32 s51, v247, 59
	global_load_dwordx4 v[60:63], v[24:25], off
	s_branch .Ltc_first
.Ltc_first:
	s_waitcnt vmcnt(0)
	s_branch .Ltc_copy
.Ltc_top:
	s_waitcnt vmcnt(3)
.Ltc_copy:
	v_mov_b64_e32 v[40:41], v[0:1]
	v_mov_b64_e32 v[42:43], v[2:3]
	v_mov_b64_e32 v[48:49], v[14:15]
	v_mov_b64_e32 v[50:51], v[16:17]
	v_mov_b64_e32 v[52:53], v[18:19]
	v_mov_b64_e32 v[54:55], v[20:21]
	v_mov_b64_e32 v[56:57], v[10:11]
	v_mov_b64_e32 v[58:59], v[22:23]
	v_mov_b64_e32 v[64:65], v[60:61]
	v_mov_b64_e32 v[66:67], v[62:63]
	s_mov_b64 s[56:57], s[6:7]
	s_add_i32 s2, s2, s70
	v_readlane_b32 s4, v246, 13
	s_cmp_lt_i32 s2, s4
	s_cbranch_scc0 .Ltc_body
	s_ashr_i32 s17, s2, 8
	s_ashr_i32 s4, s17, 31
	v_readlane_b32 s6, v246, 8
	s_add_u32 s6, s6, s17
	v_readlane_b32 s7, v246, 12
	s_addc_u32 s7, s7, s4
	s_nop 0
	v_cmp_gt_i64_e32 vcc, s[6:7], v[8:9]
	s_cbranch_vccnz .Ltcl_823
	s_ashr_i32 s4, s6, 31
	s_lshr_b32 s4, s4, 29
	s_add_i32 s4, s6, s4
	s_and_b32 s7, s4, -8
	s_sub_i32 s10, s6, s7
	s_cmp_gt_i32 s10, 3
	s_mov_b64 s[6:7], -1
	s_cbranch_scc0 .Ltcl_820
	s_mul_i32 s6, s10, 0x44
	s_add_i32 s11, s6, 4
	s_mov_b64 s[6:7], 0

; DI unsigned pk2(float lo, float hi) { f32x2 v = {lo, hi}; bf16x2_t b = __builtin_convertvector(v, bf16x2_t); return __builtin_bit_cast(unsigned, b); }
; DI void tail_combine(const Prm& p, int Mg, int Ng, const float* part, float alpha, int from_inputs, bf16_t* xn, const float* gnext, float* rss, int gw, int ngw, int lane) {
;     ...
;         for (int kz = 0; kz < TAIL_KS; ++kz) x = x + *(const f32x4*)(part + (size_t)(j * TAIL_KS + kz) * 65536 + rr * 256 + 4 * lane) * alpha;
;         *(f32x4*)(xrow(p, r) + col) = x;
;         if (xn) { const f32x4 g = *(const f32x4*)(gnext + col); u32x2 w; w.x = pk2(x.x * g.x, x.y * g.y); w.y = pk2(x.z * g.z, x.w * g.w); *(u32x2*)(xn + (size_t)r * D + col) = w;
;             const float ss = wave_sum(x.x * x.x + x.y * x.y + x.z * x.z + x.w * x.w); if (lane == 0) atomicAdd(rss + r, ss); } }
.Ltc_body:
	s_nop 0
	v_pk_fma_f32 v[42:43], v[50:51], 0.5, v[42:43] op_sel_hi:[1,0,1]
	v_pk_fma_f32 v[40:41], v[48:49], 0.5, v[40:41] op_sel_hi:[1,0,1]
	s_nop 0
	v_pk_fma_f32 v[42:43], v[54:55], 0.5, v[42:43] op_sel_hi:[1,0,1]
	v_pk_fma_f32 v[40:41], v[52:53], 0.5, v[40:41] op_sel_hi:[1,0,1]
	global_store_dwordx4 v[58:59], v[40:43], off
	s_nop 0
	v_mul_f32_e32 v44, v41, v41
	v_fmac_f32_e32 v44, v40, v40
	v_fmac_f32_e32 v44, v42, v42
	v_fmac_f32_e32 v44, v43, v43
	s_nop 0
	v_pk_mul_f32 v[42:43], v[42:43], v[66:67]
	v_add_f32_dpp v44, v44, v44 quad_perm:[1,0,3,2] row_mask:0xf bank_mask:0xf bound_ctrl:1
	v_pk_mul_f32 v[40:41], v[40:41], v[64:65]
	s_nop 0
	v_add_f32_dpp v44, v44, v44 quad_perm:[2,3,0,1] row_mask:0xf bank_mask:0xf bound_ctrl:1
	v_cvt_pk_bf16_f32 v40, v40, v41
	v_cvt_pk_bf16_f32 v41, v42, v43
	v_add_f32_dpp v44, v44, v44 row_half_mirror row_mask:0xf bank_mask:0xf bound_ctrl:1
	global_store_dwordx2 v[56:57], v[40:41], off
	s_nop 0
	v_add_f32_dpp v44, v44, v44 row_mirror row_mask:0xf bank_mask:0xf bound_ctrl:1
	s_nop 0
	v_readlane_b32 s4, v44, 0
	v_readlane_b32 s18, v44, 16
	v_readlane_b32 s17, v44, 32
	v_readlane_b32 s19, v44, 48
	s_and_saveexec_b64 s[10:11], s[0:1]
	s_cbranch_execz .Ltc_join
	s_mov_b64 s[12:13], exec
	v_mbcnt_lo_u32_b32 v40, s12, 0
	v_mbcnt_hi_u32_b32 v40, s13, v40
	v_cmp_eq_u32_e32 vcc, 0, v40
	s_and_b64 s[20:21], exec, vcc
	s_mov_b64 exec, s[20:21]
	s_cbranch_execz .Ltc_join
	s_lshl_b64 s[56:57], s[56:57], 2
	s_add_u32 s56, s8, s56
	v_mov_b32_e32 v40, s18
	v_mov_b32_e32 v41, s19
	s_addc_u32 s57, s9, s57
	v_add_f32_e32 v40, s4, v40
	v_add_f32_e32 v41, s17, v41
	s_bcnt1_i32_b64 s4, s[12:13]
	v_add_f32_e32 v40, v40, v41
	v_cvt_f32_ubyte0_e32 v41, s4
	v_mul_f32_e32 v40, v40, v41
	global_atomic_add_f32 v5, v40, s[56:57]
.Ltc_join:
	s_or_b64 exec, exec, s[10:11]
	v_readlane_b32 s4, v246, 13
	s_cmp_lt_i32 s2, s4
	s_cbranch_scc1 .Ltc_top

; DI void tail_combine(const Prm& p, int Mg, int Ng, const float* part, float alpha, int from_inputs, bf16_t* xn, const float* gnext, float* rss, int gw, int ngw, int lane) {
;     ...
;     for (int it = gw; it < ntail * 256; it += ngw) { const int j = it >> 8, rr = it & 255; pg8::Unit u; S.mapL((long)base * S.G + j, u);
;         const int r = u.pm * 256 + rr, col = u.pn * 256 + 4 * lane; const float* srcp = from_inputs ? x0row(p, r) : xrow(p, r);
;         f32x4 x = srcp ? *(const f32x4*)(srcp + col) : (f32x4){0.f, 0.f, 0.f, 0.f};
; #pragma unroll
;         for (int kz = 0; kz < TAIL_KS; ++kz) x = x + *(const f32x4*)(part + (size_t)(j * TAIL_KS + kz) * 65536 + rr * 256 + 4 * lane) * alpha;
;         *(f32x4*)(xrow(p, r) + col) = x;
.Ltdp_2571:
	s_lshl_b32 s8, s0, 1
	s_lshl_b32 s0, s2, 10
	s_ashr_i32 s9, s8, 31
	v_lshl_add_u64 v[16:17], v[4:5], 0, s[0:1]
	s_lshl_b64 s[2:3], s[8:9], 18
	v_lshl_add_u64 v[12:13], v[16:17], 0, s[2:3]
	s_or_b32 s2, s8, 1
	s_ashr_i32 s3, s2, 31
	s_lshl_b64 s[2:3], s[2:3], 18
	global_load_dwordx4 v[12:15], v[12:13], off
	v_lshl_add_u64 v[16:17], v[16:17], 0, s[2:3]
	global_load_dwordx4 v[16:19], v[16:17], off
	s_branch .Ltd_first

; DI void tail_combine(const Prm& p, int Mg, int Ng, const float* part, float alpha, int from_inputs, bf16_t* xn, const float* gnext, float* rss, int gw, int ngw, int lane) {
;     ...
;     for (int it = gw; it < ntail * 256; it += ngw) { const int j = it >> 8, rr = it & 255; pg8::Unit u; S.mapL((long)base * S.G + j, u);
;         const int r = u.pm * 256 + rr, col = u.pn * 256 + 4 * lane; const float* srcp = from_inputs ? x0row(p, r) : xrow(p, r);
;         f32x4 x = srcp ? *(const f32x4*)(srcp + col) : (f32x4){0.f, 0.f, 0.f, 0.f};
; #pragma unroll
;         for (int kz = 0; kz < TAIL_KS; ++kz) x = x + *(const f32x4*)(part + (size_t)(j * TAIL_KS + kz) * 65536 + rr * 256 + 4 * lane) * alpha;
;         *(f32x4*)(xrow(p, r) + col) = x;
.Ltdp_2577:
	v_mov_b32_e32 v0, 0
	v_mov_b32_e32 v1, v0
	v_mov_b32_e32 v2, v0
	v_mov_b32_e32 v3, v0
	s_branch .Ltdp_2571
.Ltd_first:
	s_waitcnt vmcnt(0)
	s_branch .Ltd_copy
.Ltd_top:
	s_waitcnt vmcnt(1)
.Ltd_copy:
	v_mov_b64_e32 v[20:21], v[0:1]
	v_mov_b64_e32 v[22:23], v[2:3]
	v_mov_b64_e32 v[24:25], v[12:13]
	v_mov_b64_e32 v[26:27], v[14:15]
	v_mov_b64_e32 v[28:29], v[16:17]
	v_mov_b64_e32 v[30:31], v[18:19]
	v_mov_b64_e32 v[32:33], v[8:9]
	s_add_i32 s4, s4, s70
	v_readlane_b32 s0, v246, 13
	s_cmp_lt_i32 s4, s0
	s_cbranch_scc0 .Ltd_body
	s_branch .Ltdl_2572

; DI void tail_combine(const Prm& p, int Mg, int Ng, const float* part, float alpha, int from_inputs, bf16_t* xn, const float* gnext, float* rss, int gw, int ngw, int lane) {
;     ...
;         for (int kz = 0; kz < TAIL_KS; ++kz) x = x + *(const f32x4*)(part + (size_t)(j * TAIL_KS + kz) * 65536 + rr * 256 + 4 * lane) * alpha;
;         *(f32x4*)(xrow(p, r) + col) = x;
.Ltd_body:
	v_pk_fma_f32 v[22:23], v[26:27], 0.5, v[22:23] op_sel_hi:[1,0,1]
	v_pk_fma_f32 v[20:21], v[24:25], 0.5, v[20:21] op_sel_hi:[1,0,1]
	v_pk_fma_f32 v[22:23], v[30:31], 0.5, v[22:23] op_sel_hi:[1,0,1]
	v_pk_fma_f32 v[20:21], v[28:29], 0.5, v[20:21] op_sel_hi:[1,0,1]
	global_store_dwordx4 v[32:33], v[20:23], off
	v_readlane_b32 s0, v246, 13
	s_cmp_lt_i32 s4, s0
	s_cbranch_scc1 .Ltd_top
